# MLA loop: DMA vmcnt(0) wait moved to end of VALU half; first 16 V transposed LDS reads issued before the half-step barrier
# speedup vs baseline: 1.0026x; 1.0014x over previous
.LBB0_311:
	v_cndmask_b32_e64 v84, v148, 1.0, s[8:9]
	v_add_f32_e32 v148, v82, v83
	v_fmac_f32_e32 v148, v219, v84
	v_add_u32_e32 v219, s17, v182
	s_waitcnt vmcnt(0)
	ds_read_b64_tr_b16 v[82:83], v219 offset:0
	ds_read_b64_tr_b16 v[84:85], v219 offset:0x800
	ds_read_b64_tr_b16 v[86:87], v219 offset:0x1000
	ds_read_b64_tr_b16 v[88:89], v219 offset:0x1800
	ds_read_b64_tr_b16 v[90:91], v219 offset:0x2000
	ds_read_b64_tr_b16 v[92:93], v219 offset:0x2800
	ds_read_b64_tr_b16 v[94:95], v219 offset:0x3000
	ds_read_b64_tr_b16 v[96:97], v219 offset:0x3800
	ds_read_b64_tr_b16 v[220:221], v219 offset:0x200
	ds_read_b64_tr_b16 v[222:223], v219 offset:0xa00
	ds_read_b64_tr_b16 v[224:225], v219 offset:0x1200
	ds_read_b64_tr_b16 v[226:227], v219 offset:0x1a00
	ds_read_b64_tr_b16 v[228:229], v219 offset:0x2200
	ds_read_b64_tr_b16 v[230:231], v219 offset:0x2a00
	s_add_i32 s8, s16, 0x6000
	ds_read_b64_tr_b16 v[232:233], v219 offset:0x3200
	s_cmpk_lg_u32 s16, 0xc000
	ds_read_b64_tr_b16 v[234:235], v219 offset:0x3a00
	s_barrier
	s_cselect_b32 s16, s8, 0
	s_add_i32 s8, s14, 0x6000
	s_waitcnt lgkmcnt(8)
	s_cmpk_lg_u32 s14, 0xc000
	s_cselect_b32 s14, s8, 0
	v_mfma_f32_32x32x16_bf16 v[50:65], v[74:77], v[82:85], v[50:65]
	v_mfma_f32_32x32x16_bf16 v[50:65], v[78:81], v[86:89], v[50:65]
	v_mfma_f32_32x32x16_bf16 v[50:65], v[70:73], v[90:93], v[50:65]
	v_mfma_f32_32x32x16_bf16 v[50:65], v[66:69], v[94:97], v[50:65]
	ds_read_b64_tr_b16 v[82:83], v219 offset:0x400
	ds_read_b64_tr_b16 v[84:85], v219 offset:0xc00
	ds_read_b64_tr_b16 v[86:87], v219 offset:0x1400
	ds_read_b64_tr_b16 v[88:89], v219 offset:0x1c00
	ds_read_b64_tr_b16 v[90:91], v219 offset:0x2400
	ds_read_b64_tr_b16 v[92:93], v219 offset:0x2c00
	ds_read_b64_tr_b16 v[94:95], v219 offset:0x3400
	ds_read_b64_tr_b16 v[96:97], v219 offset:0x3c00
	s_waitcnt lgkmcnt(8)
	v_mfma_f32_32x32x16_bf16 v[34:49], v[74:77], v[220:223], v[34:49]
	v_mfma_f32_32x32x16_bf16 v[34:49], v[78:81], v[224:227], v[34:49]
	v_mfma_f32_32x32x16_bf16 v[34:49], v[70:73], v[228:231], v[34:49]
	v_mfma_f32_32x32x16_bf16 v[34:49], v[66:69], v[232:235], v[34:49]
	ds_read_b64_tr_b16 v[220:221], v219 offset:0x600
	ds_read_b64_tr_b16 v[222:223], v219 offset:0xe00
	ds_read_b64_tr_b16 v[224:225], v219 offset:0x1600
	ds_read_b64_tr_b16 v[226:227], v219 offset:0x1e00
	ds_read_b64_tr_b16 v[228:229], v219 offset:0x2600
	ds_read_b64_tr_b16 v[230:231], v219 offset:0x2e00
	ds_read_b64_tr_b16 v[232:233], v219 offset:0x3600
	ds_read_b64_tr_b16 v[234:235], v219 offset:0x3e00
	s_waitcnt lgkmcnt(8)
	v_mfma_f32_32x32x16_bf16 v[18:33], v[74:77], v[82:85], v[18:33]
	v_mfma_f32_32x32x16_bf16 v[18:33], v[78:81], v[86:89], v[18:33]
	v_mfma_f32_32x32x16_bf16 v[18:33], v[70:73], v[90:93], v[18:33]
	v_mfma_f32_32x32x16_bf16 v[18:33], v[66:69], v[94:97], v[18:33]
	s_waitcnt lgkmcnt(0)
	v_mfma_f32_32x32x16_bf16 v[2:17], v[74:77], v[220:223], v[2:17]
	s_cmp_lg_u32 s5, -1
	s_cselect_b32 s8, s5, 0
	s_add_i32 s8, s8, s16
	v_add_u32_e32 v219, s8, v178
	v_add_u32_e32 v244, s8, v179
	v_add_u32_e32 v245, s8, v180
	v_add_u32_e32 v246, s8, v181
	v_mfma_f32_32x32x16_bf16 v[2:17], v[78:81], v[224:227], v[2:17]
	v_mfma_f32_32x32x16_bf16 v[2:17], v[70:73], v[228:231], v[2:17]
	ds_read_b128 v[70:73], v219 offset:0
	ds_read_b128 v[74:77], v219 offset:0x3000
	ds_read_b128 v[220:223], v244 offset:0
	ds_read_b128 v[224:227], v244 offset:0x3000
	ds_read_b128 v[228:231], v245 offset:0
	ds_read_b128 v[236:239], v245 offset:0x3000
	s_waitcnt lgkmcnt(4)
	v_mfma_f32_32x32x16_bf16 v[2:17], v[66:69], v[232:235], v[2:17]
	v_mfma_f32_32x32x16_bf16 v[82:97], v[70:73], v[98:101], 0
	v_mfma_f32_32x32x16_bf16 v[66:81], v[74:77], v[98:101], 0
	ds_read_b128 v[232:235], v246 offset:0
	ds_read_b128 v[240:243], v246 offset:0x3000
	s_waitcnt lgkmcnt(4)
	v_mfma_f32_32x32x16_bf16 v[82:97], v[220:223], v[102:105], v[82:97]
	v_mfma_f32_32x32x16_bf16 v[66:81], v[224:227], v[102:105], v[66:81]
	ds_read_b128 v[220:223], v219 offset:0x80
	ds_read_b128 v[224:227], v219 offset:0x3080
	s_waitcnt lgkmcnt(4)
	v_mfma_f32_32x32x16_bf16 v[82:97], v[228:231], v[106:109], v[82:97]
	v_mfma_f32_32x32x16_bf16 v[66:81], v[236:239], v[106:109], v[66:81]
	ds_read_b128 v[228:231], v244 offset:0x80
	ds_read_b128 v[236:239], v244 offset:0x3080
	s_waitcnt lgkmcnt(4)
	v_mfma_f32_32x32x16_bf16 v[82:97], v[232:235], v[110:113], v[82:97]
	v_mfma_f32_32x32x16_bf16 v[66:81], v[240:243], v[110:113], v[66:81]
	ds_read_b128 v[232:235], v245 offset:0x80
	ds_read_b128 v[240:243], v245 offset:0x3080
	s_waitcnt lgkmcnt(4)
	v_mfma_f32_32x32x16_bf16 v[82:97], v[220:223], v[114:117], v[82:97]
	v_mfma_f32_32x32x16_bf16 v[66:81], v[224:227], v[114:117], v[66:81]
	ds_read_b128 v[220:223], v246 offset:0x80
	ds_read_b128 v[224:227], v246 offset:0x3080
	s_waitcnt lgkmcnt(4)
	v_mfma_f32_32x32x16_bf16 v[82:97], v[228:231], v[118:121], v[82:97]
	v_mfma_f32_32x32x16_bf16 v[66:81], v[236:239], v[118:121], v[66:81]
	ds_read_b128 v[228:231], v219 offset:0x100
	ds_read_b128 v[236:239], v219 offset:0x3100
	s_waitcnt lgkmcnt(4)
	v_mfma_f32_32x32x16_bf16 v[82:97], v[232:235], v[122:125], v[82:97]
	v_mfma_f32_32x32x16_bf16 v[66:81], v[240:243], v[122:125], v[66:81]
	ds_read_b128 v[232:235], v244 offset:0x100
	ds_read_b128 v[240:243], v244 offset:0x3100
	s_waitcnt lgkmcnt(4)
	v_mfma_f32_32x32x16_bf16 v[82:97], v[220:223], v[126:129], v[82:97]
	v_mfma_f32_32x32x16_bf16 v[66:81], v[224:227], v[126:129], v[66:81]
	ds_read_b128 v[220:223], v245 offset:0x100
	ds_read_b128 v[224:227], v245 offset:0x3100
	s_waitcnt lgkmcnt(4)
	v_mfma_f32_32x32x16_bf16 v[82:97], v[228:231], v[130:133], v[82:97]
	v_mfma_f32_32x32x16_bf16 v[66:81], v[236:239], v[130:133], v[66:81]
	ds_read_b128 v[228:231], v246 offset:0x100
	ds_read_b128 v[236:239], v246 offset:0x3100
	s_waitcnt lgkmcnt(4)
	v_mfma_f32_32x32x16_bf16 v[82:97], v[232:235], v[134:137], v[82:97]
	v_mfma_f32_32x32x16_bf16 v[66:81], v[240:243], v[134:137], v[66:81]
	s_waitcnt lgkmcnt(2)
	v_mfma_f32_32x32x16_bf16 v[82:97], v[220:223], v[138:141], v[82:97]
	v_mfma_f32_32x32x16_bf16 v[66:81], v[224:227], v[138:141], v[66:81]
	s_waitcnt lgkmcnt(0)
	v_mfma_f32_32x32x16_bf16 v[82:97], v[228:231], v[142:145], v[82:97]
	v_mfma_f32_32x32x16_bf16 v[66:81], v[236:239], v[142:145], v[66:81]
	s_waitcnt vmcnt(0)
	s_add_i32 s8, s75, 0x4000
	s_waitcnt lgkmcnt(0)
	s_barrier
	s_cmpk_lg_u32 s75, 0x8000
	s_cselect_b32 s8, s8, 0
	s_add_i32 s15, s15, 64
	s_add_i32 s12, s12, 1
	v_add_u32_e32 v215, 0x80000, v215
	v_add_u32_e32 v214, 0x80000, v214
	s_cmp_eq_u32 s28, s15
	v_subrev_u32_e32 v213, 64, v213
	s_cbranch_scc1 .LBB0_313
	v_mov_b32_e32 v220, v212
	v_mov_b32_e32 v219, v148
	s_mov_b32 s17, s75
	s_mov_b32 s75, s8
	s_branch .LBB0_303
